# P0b gain/shift/scale loads also remapped to full lines (+ v_permlane32_swap), on top of the x-row remap
# baseline (speedup 1.0000x reference)
; #define P0B_LOAD(dst_, r0_) do { _Pragma("unroll") for (int rr = 0; rr < 2; ++rr) { const int row = min((r0_) + rr * NGW, NTOK - 1); \
;             const float* xr = row < NP ? P.xp + (size_t)row * DM : P.xs + (size_t)(row - NP) * DM; \
;             _Pragma("unroll") for (int j = 0; j < 4; ++j) dst_[rr][j] = *(const f32x4*)(xr + 8 * lane + 512 * (j >> 1) + 4 * (j & 1)); } } while (0)
; __device__ __forceinline__ void phase0b(const Params& P, int lane, int wave, int bid, int G) {
;     const float* mod = (const float*)(P.ws + OFF_MOD); bf16_t* H = (bf16_t*)(P.ws + OFF_H);
;     const int gw = bid * 8 + wave, NGW = G * 8;
;     f32x4 v[2][4], vn[2][4];
;     ...
;     P0B_LOAD(v, gw);
.LBB0_90:
	s_cmp_lt_i32 s28, 2
	s_cselect_b64 s[0:1], -1, 0
	s_and_b64 s[4:5], s[0:1], s[6:7]
	s_andn2_b64 vcc, exec, s[4:5]
	s_cbranch_vccnz .LBB0_96
	s_lshl_b32 s16, s2, 3
	s_add_i32 s6, s97, s16
	s_cmp_gt_i32 s6, 0x13fff
	s_cbranch_scc1 .LBB0_96
	s_add_u32 s17, s22, 0x10000
	s_addc_u32 s18, s23, 0
	s_lshl_b32 s5, s3, 3
	s_add_i32 s5, s5, s6
	s_min_i32 s7, s5, 0x13fff
	s_lshl_b32 s4, s3, 4
	s_ashr_i32 s10, s7, 31
	s_add_i32 s12, s7, 0xffff0000
	s_cmp_lt_i32 s5, 0x10000
	s_cselect_b32 s11, s10, 0
	s_cselect_b32 s10, s7, s12
	s_cselect_b32 s5, s37, s39
	s_cselect_b32 s13, s36, s38
	s_lshl_b64 s[10:11], s[10:11], 12
	s_add_u32 s10, s13, s10
	s_addc_u32 s11, s5, s11
	s_ashr_i32 s7, s6, 31
	s_add_i32 s5, s6, 0xffff0000
	s_cmp_lt_i32 s6, 0x10000
	s_cselect_b32 s13, s7, 0
	s_cselect_b32 s12, s6, s5
	s_cselect_b32 s14, s37, s39
	s_cselect_b32 s15, s36, s38
	s_lshl_b64 s[12:13], s[12:13], 12
	s_add_u32 s12, s15, s12
	v_lshlrev_b32_e32 v10, 5, v180
	v_and_b32_e32 v120, 31, v180
	v_lshlrev_b32_e32 v120, 5, v120
	v_lshrrev_b32_e32 v121, 5, v180
	v_lshl_or_b32 v120, v121, 4, v120
	s_addc_u32 s13, s14, s13
	global_load_dwordx4 v[50:53], v120, s[12:13] offset:3072
	global_load_dwordx4 v[54:57], v120, s[12:13] offset:2048
	global_load_dwordx4 v[58:61], v120, s[12:13] offset:1024
	global_load_dwordx4 v[62:65], v120, s[12:13]
	global_load_dwordx4 v[2:5], v120, s[10:11] offset:3072
	global_load_dwordx4 v[6:9], v120, s[10:11] offset:2048
	global_load_dwordx4 v[42:45], v120, s[10:11] offset:1024
	global_load_dwordx4 v[46:49], v120, s[10:11]
	s_lshl_b64 s[6:7], s[6:7], 11
	v_mov_b32_e32 v11, 0
	s_add_u32 s6, s22, s6
	v_lshlrev_b32_e32 v66, 3, v180
	v_lshl_add_u64 v[68:69], s[44:45], 0, v[10:11]
	v_mov_b32_e32 v121, 0
	v_lshl_add_u64 v[122:123], s[44:45], 0, v[120:121]
	v_lshlrev_b32_e32 v10, 4, v180
	s_addc_u32 s7, s23, s7
	s_ashr_i32 s5, s4, 31
	v_or_b32_e32 v12, 0x200, v66
	v_lshl_add_u64 v[14:15], s[22:23], 0, v[10:11]
	s_mov_b64 s[10:11], 0x2000000
	v_lshl_add_u64 v[10:11], s[6:7], 0, v[10:11]
	s_lshl_b64 s[6:7], s[4:5], 11
	s_add_i32 s5, s2, s3
	s_mul_i32 s19, s3, 24
	v_mbcnt_lo_u32_b32 v1, -1, 0
	v_lshl_add_u64 v[70:71], v[14:15], 0, s[10:11]
	v_lshl_add_u64 v[72:73], v[10:11], 0, s[10:11]
	s_lshl_b32 s5, s5, 3
	s_add_i32 s19, s19, s16
	s_add_i32 s20, s4, s16
	v_mbcnt_hi_u32_b32 v1, -1, v1
	v_mov_b32_e32 v67, 0x358637bd
	s_mov_b32 s21, 0x800000
	v_lshlrev_b32_e32 v74, 2, v12
	s_mov_b32 s24, s97
	s_waitcnt vmcnt(0)
	s_nop 1
	v_permlane32_swap_b32_e32 v62, v58
	v_permlane32_swap_b32_e32 v63, v59
	v_permlane32_swap_b32_e32 v64, v60
	v_permlane32_swap_b32_e32 v65, v61
	v_permlane32_swap_b32_e32 v54, v50
	v_permlane32_swap_b32_e32 v55, v51
	v_permlane32_swap_b32_e32 v56, v52
	v_permlane32_swap_b32_e32 v57, v53
	v_permlane32_swap_b32_e32 v46, v42
	v_permlane32_swap_b32_e32 v47, v43
	v_permlane32_swap_b32_e32 v48, v44
	v_permlane32_swap_b32_e32 v49, v45
	v_permlane32_swap_b32_e32 v6, v2
	v_permlane32_swap_b32_e32 v7, v3
	v_permlane32_swap_b32_e32 v8, v4
	v_permlane32_swap_b32_e32 v9, v5
	s_branch .LBB0_94

; #define P0B_LOAD(dst_, r0_) do { _Pragma("unroll") for (int rr = 0; rr < 2; ++rr) { const int row = min((r0_) + rr * NGW, NTOK - 1); \
;             const float* xr = row < NP ? P.xp + (size_t)row * DM : P.xs + (size_t)(row - NP) * DM; \
;             _Pragma("unroll") for (int j = 0; j < 4; ++j) dst_[rr][j] = *(const f32x4*)(xr + 8 * lane + 512 * (j >> 1) + 4 * (j & 1)); } } while (0)
; __device__ __forceinline__ void phase0b(const Params& P, int lane, int wave, int bid, int G) {
;     ...
;     for (int row0 = gw; row0 < NTOK; row0 += 2 * NGW) {
;         P0B_LOAD(vn, row0 + 2 * NGW);
;         asm volatile("" ::: "memory");
;         float ss[2];
; #pragma unroll
;         for (int rr = 0; rr < 2; ++rr) { float s2 = 0.f;
; #pragma unroll
;             for (int j = 0; j < 4; ++j) s2 += (v[rr][j].x * v[rr][j].x + v[rr][j].y * v[rr][j].y) + (v[rr][j].z * v[rr][j].z + v[rr][j].w * v[rr][j].w);
;             ss[rr] = s2; }
; #pragma unroll
;         for (int rr = 0; rr < 2; ++rr) { const int row = row0 + rr * NGW; if (row >= NTOK) break;
;             const int s = row < NP ? (row >> 12) : 16; const float* md = mod + s * 3072;
;             const float rstd = rsqrtf(wave_sum(ss[rr]) * (1.f / DM) + EPS);
; #pragma unroll
;             for (int jj = 0; jj < 2; ++jj) { const int c = 8 * lane + 512 * jj; f32x4 hv[2];
; #pragma unroll
;                 for (int e = 0; e < 2; ++e) { const f32x4 gn = *(const f32x4*)(P.norm_gain + c + 4 * e), sh = *(const f32x4*)(md + c + 4 * e), scv = *(const f32x4*)(md + 1024 + c + 4 * e);
;                     hv[e] = (v[rr][2 * jj + e] * rstd * gn) * (scv + 1.f) + sh; }
.LBB0_94:
	s_add_i32 s10, s20, s24
	s_min_i32 s13, s10, 0x13fff
	s_add_i32 s12, s16, s24
	s_add_i32 s14, s13, 0xffff0000
	s_ashr_i32 s11, s13, 31
	s_cmp_lt_i32 s10, 0x10000
	s_cselect_b32 s11, s11, 0
	s_cselect_b32 s10, s13, s14
	s_cselect_b32 s13, s37, s39
	s_cselect_b32 s14, s36, s38
	s_lshl_b64 s[10:11], s[10:11], 12
	s_add_u32 s10, s14, s10
	s_addc_u32 s11, s13, s11
	v_lshlrev_b32_e32 v75, 2, v66
	global_load_dwordx4 v[14:17], v120, s[10:11] offset:1024
	global_load_dwordx4 v[22:25], v120, s[10:11]
	global_load_dwordx4 v[10:13], v120, s[10:11] offset:3072
	global_load_dwordx4 v[18:21], v120, s[10:11] offset:2048
	s_add_i32 s10, s19, s24
	s_min_i32 s13, s10, 0x13fff
	s_ashr_i32 s11, s13, 31
	s_add_i32 s14, s13, 0xffff0000
	s_cmp_lt_i32 s10, 0x10000
	s_cselect_b32 s11, s11, 0
	s_cselect_b32 s10, s13, s14
	s_cselect_b32 s13, s37, s39
	s_cselect_b32 s14, s36, s38
	s_lshl_b64 s[10:11], s[10:11], 12
	s_add_u32 s10, s14, s10
	s_addc_u32 s11, s13, s11
	s_waitcnt vmcnt(8)
	v_pk_mul_f32 v[76:77], v[64:65], v[64:65]
	v_pk_mul_f32 v[78:79], v[62:63], v[62:63]
	global_load_dwordx4 v[30:33], v120, s[10:11] offset:1024
	global_load_dwordx4 v[38:41], v120, s[10:11]
	global_load_dwordx4 v[26:29], v120, s[10:11] offset:3072
	global_load_dwordx4 v[34:37], v120, s[10:11] offset:2048
	v_pk_mov_b32 v[80:81], v[78:79], v[76:77] op_sel:[1,0]
	v_mov_b32_e32 v79, v77
	s_min_i32 s10, s12, 0x10000
	v_pk_add_f32 v[76:77], v[80:81], v[78:79]
	v_pk_mul_f32 v[78:79], v[60:61], v[60:61]
	v_pk_mul_f32 v[80:81], v[58:59], v[58:59]
	s_ashr_i32 s10, s10, 12
	v_pk_mov_b32 v[82:83], v[80:81], v[78:79] op_sel:[1,0]
	v_mov_b32_e32 v81, v79
	s_mulk_i32 s10, 0xc00
	v_pk_add_f32 v[78:79], v[82:83], v[80:81]
	s_ashr_i32 s11, s10, 31
	v_mul_f32_e32 v80, v50, v50
	v_mul_f32_e32 v81, v51, v51
	v_pk_add_f32 v[76:77], v[76:77], v[76:77] op_sel:[0,1] op_sel_hi:[1,0]
	v_pk_add_f32 v[78:79], v[78:79], v[78:79] op_sel:[0,1] op_sel_hi:[1,0]
	s_lshl_b64 s[10:11], s[10:11], 2
	v_mov_b32_e32 v77, v80
	v_mov_b32_e32 v79, v81
	s_add_u32 s10, s17, s10
	v_pk_add_f32 v[76:77], v[76:77], v[78:79]
	v_mul_f32_e32 v78, v55, v55
	v_mul_f32_e32 v80, v57, v57
	s_addc_u32 s11, s18, s11
	v_mul_f32_e32 v82, v52, v52
	v_mul_f32_e32 v83, v53, v53
	v_pk_fma_f32 v[78:79], v[54:55], v[54:55], v[78:79] op_sel_hi:[1,1,0]
	v_pk_fma_f32 v[80:81], v[56:57], v[56:57], v[80:81] op_sel_hi:[1,1,0]
	s_add_u32 s12, s10, 0x1000
	v_mov_b32_e32 v79, v82
	v_mov_b32_e32 v81, v83
	s_addc_u32 s13, s11, 0
	global_load_dwordx4 v[82:85], v[122:123], off offset:1024
	global_load_dwordx4 v[86:89], v[122:123], off
	global_load_dwordx4 v[90:93], v120, s[12:13] offset:1024
	global_load_dwordx4 v[94:97], v120, s[12:13]
	global_load_dwordx4 v[98:101], v120, s[10:11] offset:1024
	global_load_dwordx4 v[102:105], v120, s[10:11]
	v_pk_add_f32 v[78:79], v[78:79], v[80:81]
	s_nop 0
	v_pk_add_f32 v[76:77], v[76:77], v[78:79]
	s_nop 0
	v_add_f32_e32 v77, v76, v77
	v_and_b32_e32 v76, 64, v1
	v_add_u32_e32 v81, 64, v76
	v_xor_b32_e32 v76, 1, v1
	v_cmp_lt_i32_e32 vcc, v76, v81
	s_nop 1
	v_cndmask_b32_e32 v76, v1, v76, vcc
	v_lshlrev_b32_e32 v76, 2, v76
	ds_bpermute_b32 v78, v76, v77
	s_waitcnt lgkmcnt(0)
	v_add_f32_e32 v78, v77, v78
	v_xor_b32_e32 v77, 2, v1
	v_cmp_lt_i32_e32 vcc, v77, v81
	s_nop 1
	v_cndmask_b32_e32 v77, v1, v77, vcc
	v_lshlrev_b32_e32 v77, 2, v77
	ds_bpermute_b32 v79, v77, v78
	s_waitcnt lgkmcnt(0)
	v_add_f32_e32 v79, v78, v79
	v_xor_b32_e32 v78, 4, v1
	v_cmp_lt_i32_e32 vcc, v78, v81
	s_nop 1
	v_cndmask_b32_e32 v78, v1, v78, vcc
	v_lshlrev_b32_e32 v78, 2, v78
	ds_bpermute_b32 v80, v78, v79
	s_waitcnt lgkmcnt(0)
	v_add_f32_e32 v80, v79, v80
	v_xor_b32_e32 v79, 8, v1
	v_cmp_lt_i32_e32 vcc, v79, v81
	s_nop 1
	v_cndmask_b32_e32 v79, v1, v79, vcc
	v_lshlrev_b32_e32 v79, 2, v79
	ds_bpermute_b32 v106, v79, v80
	s_waitcnt lgkmcnt(0)
	v_add_f32_e32 v106, v80, v106
	v_xor_b32_e32 v80, 16, v1
	v_cmp_lt_i32_e32 vcc, v80, v81
	s_nop 1
	v_cndmask_b32_e32 v80, v1, v80, vcc
	v_lshlrev_b32_e32 v80, 2, v80
	ds_bpermute_b32 v107, v80, v106
	s_waitcnt lgkmcnt(0)
	v_add_f32_e32 v106, v106, v107
	v_xor_b32_e32 v107, 32, v1
	v_cmp_lt_i32_e32 vcc, v107, v81
	s_nop 1
	v_cndmask_b32_e32 v81, v1, v107, vcc
	v_lshlrev_b32_e32 v81, 2, v81
	ds_bpermute_b32 v107, v81, v106
	s_waitcnt lgkmcnt(0)
	v_add_f32_e32 v106, v106, v107
	v_fmamk_f32 v106, v106, 0x3a800000, v67
	v_mul_f32_e32 v107, 0x4b800000, v106
	v_cmp_gt_f32_e32 vcc, s21, v106
	s_nop 1
	v_cndmask_b32_e32 v106, v106, v107, vcc
	v_rsq_f32_e32 v106, v106
	s_nop 0
	v_mul_f32_e32 v107, 0x45800000, v106
	v_cndmask_b32_e32 v106, v106, v107, vcc
	v_pk_mul_f32 v[60:61], v[60:61], v[106:107] op_sel_hi:[1,0]
	v_pk_mul_f32 v[58:59], v[58:59], v[106:107] op_sel_hi:[1,0]
	v_pk_mul_f32 v[64:65], v[64:65], v[106:107] op_sel_hi:[1,0]
	v_pk_mul_f32 v[62:63], v[62:63], v[106:107] op_sel_hi:[1,0]
	s_waitcnt vmcnt(0)
	v_permlane32_swap_b32_e32 v86, v82
	v_permlane32_swap_b32_e32 v87, v83
	v_permlane32_swap_b32_e32 v88, v84
	v_permlane32_swap_b32_e32 v89, v85
	v_permlane32_swap_b32_e32 v94, v90
	v_permlane32_swap_b32_e32 v95, v91
	v_permlane32_swap_b32_e32 v96, v92
	v_permlane32_swap_b32_e32 v97, v93
	v_permlane32_swap_b32_e32 v102, v98
	v_permlane32_swap_b32_e32 v103, v99
	v_permlane32_swap_b32_e32 v104, v100
	v_permlane32_swap_b32_e32 v105, v101
	s_waitcnt vmcnt(5)
	v_pk_mul_f32 v[58:59], v[82:83], v[58:59]
	v_pk_mul_f32 v[60:61], v[84:85], v[60:61]
	s_waitcnt vmcnt(3)
	v_pk_add_f32 v[82:83], v[92:93], 1.0 op_sel_hi:[1,0]
	v_pk_add_f32 v[84:85], v[90:91], 1.0 op_sel_hi:[1,0]
	v_pk_mul_f32 v[62:63], v[86:87], v[62:63]
	v_pk_mul_f32 v[64:65], v[88:89], v[64:65]
	s_waitcnt vmcnt(2)
; __device__ __forceinline__ unsigned cvt_pk_bf16(float lo, float hi) { unsigned r; asm volatile("v_cvt_pk_bf16_f32 %0, %1, %2" : "=v"(r) : "v"(lo), "v"(hi)); return r; }
; __device__ __forceinline__ void phase0b(const Params& P, int lane, int wave, int bid, int G) {
;     ...
;             for (int jj = 0; jj < 2; ++jj) { const int c = 8 * lane + 512 * jj; f32x4 hv[2];
; #pragma unroll
;                 for (int e = 0; e < 2; ++e) { const f32x4 gn = *(const f32x4*)(P.norm_gain + c + 4 * e), sh = *(const f32x4*)(md + c + 4 * e), scv = *(const f32x4*)(md + 1024 + c + 4 * e);
;                     hv[e] = (v[rr][2 * jj + e] * rstd * gn) * (scv + 1.f) + sh; }
;                 u32x4 o; o.x = cvt_pk_bf16(hv[0].x, hv[0].y); o.y = cvt_pk_bf16(hv[0].z, hv[0].w); o.z = cvt_pk_bf16(hv[1].x, hv[1].y); o.w = cvt_pk_bf16(hv[1].z, hv[1].w);
;                 *(u32x4*)(H + (size_t)row * DM + c) = o; } }
; #pragma unroll
;         for (int rr = 0; rr < 2; ++rr)
; #pragma unroll
;             for (int j = 0; j < 4; ++j) v[rr][j] = vn[rr][j];
	v_pk_add_f32 v[86:87], v[96:97], 1.0 op_sel_hi:[1,0]
	v_pk_add_f32 v[88:89], v[94:95], 1.0 op_sel_hi:[1,0]
	s_waitcnt vmcnt(1)
	v_pk_fma_f32 v[82:83], v[82:83], v[60:61], v[100:101]
	v_pk_fma_f32 v[60:61], v[84:85], v[58:59], v[98:99]
	s_waitcnt vmcnt(0)
	v_pk_fma_f32 v[64:65], v[86:87], v[64:65], v[104:105]
	v_pk_fma_f32 v[62:63], v[88:89], v[62:63], v[102:103]
	v_pk_mul_f32 v[56:57], v[56:57], v[106:107] op_sel_hi:[1,0]
	v_cvt_pk_bf16_f32 v58, v62, v63
	v_cvt_pk_bf16_f32 v59, v64, v65
	v_cvt_pk_bf16_f32 v60, v60, v61
	v_cvt_pk_bf16_f32 v61, v82, v83
	global_store_dwordx4 v[72:73], v[58:61], off
	global_load_dwordx4 v[58:61], v[122:123], off offset:2048
	s_nop 0
	global_load_dwordx4 v[62:65], v120, s[12:13] offset:2048
	global_load_dwordx4 v[82:85], v[122:123], off offset:3072
	global_load_dwordx4 v[86:89], v120, s[12:13] offset:3072
	global_load_dwordx4 v[90:93], v120, s[10:11] offset:2048
	global_load_dwordx4 v[94:97], v120, s[10:11] offset:3072
	v_pk_mul_f32 v[54:55], v[54:55], v[106:107] op_sel_hi:[1,0]
	v_pk_mul_f32 v[52:53], v[52:53], v[106:107] op_sel_hi:[1,0]
	v_pk_mul_f32 v[50:51], v[50:51], v[106:107] op_sel_hi:[1,0]
	s_add_i32 s12, s5, s24
	s_cmp_gt_i32 s12, 0x13fff
	s_waitcnt vmcnt(0)
	v_permlane32_swap_b32_e32 v58, v82
	v_permlane32_swap_b32_e32 v59, v83
	v_permlane32_swap_b32_e32 v60, v84
	v_permlane32_swap_b32_e32 v61, v85
	v_permlane32_swap_b32_e32 v62, v86
	v_permlane32_swap_b32_e32 v63, v87
	v_permlane32_swap_b32_e32 v64, v88
	v_permlane32_swap_b32_e32 v65, v89
	v_permlane32_swap_b32_e32 v90, v94
	v_permlane32_swap_b32_e32 v91, v95
	v_permlane32_swap_b32_e32 v92, v96
	v_permlane32_swap_b32_e32 v93, v97
	s_waitcnt vmcnt(5)
	v_pk_mul_f32 v[54:55], v[58:59], v[54:55]
	v_pk_mul_f32 v[56:57], v[60:61], v[56:57]
	s_waitcnt vmcnt(4)
	v_pk_add_f32 v[58:59], v[64:65], 1.0 op_sel_hi:[1,0]
	v_pk_add_f32 v[60:61], v[62:63], 1.0 op_sel_hi:[1,0]
	s_waitcnt vmcnt(3)
	v_pk_mul_f32 v[50:51], v[50:51], v[82:83]
	v_pk_mul_f32 v[52:53], v[52:53], v[84:85]
	s_waitcnt vmcnt(2)
	v_pk_add_f32 v[62:63], v[88:89], 1.0 op_sel_hi:[1,0]
	v_pk_add_f32 v[64:65], v[86:87], 1.0 op_sel_hi:[1,0]
	s_waitcnt vmcnt(1)
	v_pk_fma_f32 v[56:57], v[56:57], v[58:59], v[92:93]
	s_waitcnt vmcnt(0)
	v_pk_fma_f32 v[58:59], v[52:53], v[62:63], v[96:97]
	v_pk_fma_f32 v[52:53], v[50:51], v[64:65], v[94:95]
	v_pk_fma_f32 v[54:55], v[54:55], v[60:61], v[90:91]
	s_nop 0
	v_cvt_pk_bf16_f32 v50, v54, v55
	v_cvt_pk_bf16_f32 v51, v56, v57
	v_cvt_pk_bf16_f32 v52, v52, v53
	v_cvt_pk_bf16_f32 v53, v58, v59
	global_store_dwordx4 v[72:73], v[50:53], off offset:1024
	s_cbranch_scc1 .LBB0_93
; __device__ __forceinline__ unsigned cvt_pk_bf16(float lo, float hi) { unsigned r; asm volatile("v_cvt_pk_bf16_f32 %0, %1, %2" : "=v"(r) : "v"(lo), "v"(hi)); return r; }
; __device__ __forceinline__ void phase0b(const Params& P, int lane, int wave, int bid, int G) {
;     ...
;         for (int rr = 0; rr < 2; ++rr) { float s2 = 0.f;
; #pragma unroll
;             for (int j = 0; j < 4; ++j) s2 += (v[rr][j].x * v[rr][j].x + v[rr][j].y * v[rr][j].y) + (v[rr][j].z * v[rr][j].z + v[rr][j].w * v[rr][j].w);
;             ss[rr] = s2; }
; #pragma unroll
;         for (int rr = 0; rr < 2; ++rr) { const int row = row0 + rr * NGW; if (row >= NTOK) break;
;             const int s = row < NP ? (row >> 12) : 16; const float* md = mod + s * 3072;
;             const float rstd = rsqrtf(wave_sum(ss[rr]) * (1.f / DM) + EPS);
; #pragma unroll
;             for (int jj = 0; jj < 2; ++jj) { const int c = 8 * lane + 512 * jj; f32x4 hv[2];
; #pragma unroll
;                 for (int e = 0; e < 2; ++e) { const f32x4 gn = *(const f32x4*)(P.norm_gain + c + 4 * e), sh = *(const f32x4*)(md + c + 4 * e), scv = *(const f32x4*)(md + 1024 + c + 4 * e);
;                     hv[e] = (v[rr][2 * jj + e] * rstd * gn) * (scv + 1.f) + sh; }
;                 u32x4 o; o.x = cvt_pk_bf16(hv[0].x, hv[0].y); o.y = cvt_pk_bf16(hv[0].z, hv[0].w); o.z = cvt_pk_bf16(hv[1].x, hv[1].y); o.w = cvt_pk_bf16(hv[1].z, hv[1].w);
;                 *(u32x4*)(H + (size_t)row * DM + c) = o; } }
	s_min_i32 s10, s12, 0x10000
	s_ashr_i32 s10, s10, 12
	s_mulk_i32 s10, 0xc00
	s_ashr_i32 s11, s10, 31
	s_lshl_b64 s[10:11], s[10:11], 2
	s_add_u32 s10, s17, s10
	s_addc_u32 s11, s18, s11
	v_pk_mul_f32 v[50:51], v[48:49], v[48:49]
	v_pk_mul_f32 v[52:53], v[46:47], v[46:47]
	s_add_u32 s14, s10, 0x1000
	v_pk_mov_b32 v[54:55], v[52:53], v[50:51] op_sel:[1,0]
	v_mov_b32_e32 v53, v51
	s_addc_u32 s15, s11, 0
	v_pk_add_f32 v[90:91], v[54:55], v[52:53]
	global_load_dwordx4 v[50:53], v[122:123], off offset:1024
	global_load_dwordx4 v[54:57], v[122:123], off
	global_load_dwordx4 v[58:61], v120, s[14:15] offset:1024
	global_load_dwordx4 v[62:65], v120, s[14:15]
	global_load_dwordx4 v[82:85], v120, s[10:11] offset:1024
	global_load_dwordx4 v[86:89], v120, s[10:11]
	v_pk_mul_f32 v[92:93], v[44:45], v[44:45]
	v_pk_mul_f32 v[94:95], v[42:43], v[42:43]
	v_pk_add_f32 v[90:91], v[90:91], v[90:91] op_sel:[0,1] op_sel_hi:[1,0]
	v_pk_mov_b32 v[96:97], v[94:95], v[92:93] op_sel:[1,0]
	v_mov_b32_e32 v95, v93
	v_pk_add_f32 v[92:93], v[96:97], v[94:95]
	v_mul_f32_e32 v94, v2, v2
	v_mul_f32_e32 v95, v3, v3
	v_pk_add_f32 v[92:93], v[92:93], v[92:93] op_sel:[0,1] op_sel_hi:[1,0]
	v_mov_b32_e32 v91, v94
	v_mov_b32_e32 v93, v95
	v_pk_add_f32 v[90:91], v[90:91], v[92:93]
	v_mul_f32_e32 v92, v7, v7
	v_mul_f32_e32 v94, v9, v9
	v_mul_f32_e32 v96, v4, v4
	v_mul_f32_e32 v97, v5, v5
	v_pk_fma_f32 v[92:93], v[6:7], v[6:7], v[92:93] op_sel_hi:[1,1,0]
	v_pk_fma_f32 v[94:95], v[8:9], v[8:9], v[94:95] op_sel_hi:[1,1,0]
	v_mov_b32_e32 v93, v96
	v_mov_b32_e32 v95, v97
	v_pk_add_f32 v[92:93], v[92:93], v[94:95]
	s_ashr_i32 s13, s12, 31
	v_pk_add_f32 v[90:91], v[90:91], v[92:93]
	s_lshl_b64 s[12:13], s[12:13], 11
	v_add_f32_e32 v90, v90, v91
	ds_bpermute_b32 v76, v76, v90
	s_waitcnt lgkmcnt(0)
	v_add_f32_e32 v76, v90, v76
	ds_bpermute_b32 v77, v77, v76
	s_waitcnt lgkmcnt(0)
	v_add_f32_e32 v76, v76, v77
	ds_bpermute_b32 v77, v78, v76
	s_waitcnt lgkmcnt(0)
	v_add_f32_e32 v76, v76, v77
	ds_bpermute_b32 v77, v79, v76
	s_waitcnt lgkmcnt(0)
	v_add_f32_e32 v76, v76, v77
	ds_bpermute_b32 v77, v80, v76
	s_waitcnt lgkmcnt(0)
	v_add_f32_e32 v76, v76, v77
	ds_bpermute_b32 v77, v81, v76
	s_waitcnt lgkmcnt(0)
	v_add_f32_e32 v76, v76, v77
	v_fmamk_f32 v76, v76, 0x3a800000, v67
	v_mul_f32_e32 v77, 0x4b800000, v76
	v_cmp_gt_f32_e32 vcc, s21, v76
	s_nop 1
	v_cndmask_b32_e32 v76, v76, v77, vcc
	v_rsq_f32_e32 v78, v76
	v_lshl_add_u64 v[76:77], v[70:71], 0, s[12:13]
	v_mul_f32_e32 v79, 0x45800000, v78
	v_cndmask_b32_e32 v78, v78, v79, vcc
	v_pk_mul_f32 v[48:49], v[48:49], v[78:79] op_sel_hi:[1,0]
	v_pk_mul_f32 v[46:47], v[46:47], v[78:79] op_sel_hi:[1,0]
	v_pk_mul_f32 v[44:45], v[44:45], v[78:79] op_sel_hi:[1,0]
	v_pk_mul_f32 v[42:43], v[42:43], v[78:79] op_sel_hi:[1,0]
	s_waitcnt vmcnt(0)
	v_permlane32_swap_b32_e32 v54, v50
	v_permlane32_swap_b32_e32 v55, v51
	v_permlane32_swap_b32_e32 v56, v52
	v_permlane32_swap_b32_e32 v57, v53
	v_permlane32_swap_b32_e32 v62, v58
	v_permlane32_swap_b32_e32 v63, v59
	v_permlane32_swap_b32_e32 v64, v60
	v_permlane32_swap_b32_e32 v65, v61
	v_permlane32_swap_b32_e32 v86, v82
	v_permlane32_swap_b32_e32 v87, v83
	v_permlane32_swap_b32_e32 v88, v84
	v_permlane32_swap_b32_e32 v89, v85
	s_waitcnt vmcnt(4)
	v_pk_mul_f32 v[46:47], v[54:55], v[46:47]
	v_pk_mul_f32 v[48:49], v[56:57], v[48:49]
	v_pk_mul_f32 v[42:43], v[50:51], v[42:43]
	v_pk_mul_f32 v[44:45], v[52:53], v[44:45]
	s_waitcnt vmcnt(2)
	v_pk_add_f32 v[50:51], v[64:65], 1.0 op_sel_hi:[1,0]
	v_pk_add_f32 v[54:55], v[60:61], 1.0 op_sel_hi:[1,0]
	v_pk_add_f32 v[56:57], v[58:59], 1.0 op_sel_hi:[1,0]
	v_pk_add_f32 v[52:53], v[62:63], 1.0 op_sel_hi:[1,0]
	s_waitcnt vmcnt(0)
	v_pk_fma_f32 v[48:49], v[50:51], v[48:49], v[88:89]
	v_pk_fma_f32 v[50:51], v[54:55], v[44:45], v[84:85]
	v_pk_fma_f32 v[44:45], v[56:57], v[42:43], v[82:83]
	v_pk_fma_f32 v[46:47], v[52:53], v[46:47], v[86:87]
	v_pk_mul_f32 v[8:9], v[8:9], v[78:79] op_sel_hi:[1,0]
	v_cvt_pk_bf16_f32 v42, v46, v47
	v_cvt_pk_bf16_f32 v43, v48, v49
	v_cvt_pk_bf16_f32 v44, v44, v45
	v_cvt_pk_bf16_f32 v45, v50, v51
	global_store_dwordx4 v[76:77], v[42:45], off
	global_load_dwordx4 v[42:45], v[122:123], off offset:2048
	s_nop 0
	global_load_dwordx4 v[46:49], v120, s[14:15] offset:2048
	global_load_dwordx4 v[50:53], v[122:123], off offset:3072
	global_load_dwordx4 v[54:57], v120, s[14:15] offset:3072
	global_load_dwordx4 v[58:61], v120, s[10:11] offset:2048
	global_load_dwordx4 v[62:65], v120, s[10:11] offset:3072
	v_pk_mul_f32 v[6:7], v[6:7], v[78:79] op_sel_hi:[1,0]
	v_pk_mul_f32 v[4:5], v[4:5], v[78:79] op_sel_hi:[1,0]
	v_pk_mul_f32 v[2:3], v[2:3], v[78:79] op_sel_hi:[1,0]
	s_waitcnt vmcnt(0)
	v_permlane32_swap_b32_e32 v42, v50
	v_permlane32_swap_b32_e32 v43, v51
	v_permlane32_swap_b32_e32 v44, v52
	v_permlane32_swap_b32_e32 v45, v53
	v_permlane32_swap_b32_e32 v46, v54
	v_permlane32_swap_b32_e32 v47, v55
	v_permlane32_swap_b32_e32 v48, v56
	v_permlane32_swap_b32_e32 v49, v57
	v_permlane32_swap_b32_e32 v58, v62
	v_permlane32_swap_b32_e32 v59, v63
	v_permlane32_swap_b32_e32 v60, v64
	v_permlane32_swap_b32_e32 v61, v65
	s_waitcnt vmcnt(5)
	v_pk_mul_f32 v[6:7], v[42:43], v[6:7]
	v_pk_mul_f32 v[8:9], v[44:45], v[8:9]
	s_waitcnt vmcnt(4)
	v_pk_add_f32 v[42:43], v[48:49], 1.0 op_sel_hi:[1,0]
	v_pk_add_f32 v[44:45], v[46:47], 1.0 op_sel_hi:[1,0]
	s_waitcnt vmcnt(3)
	v_pk_mul_f32 v[2:3], v[2:3], v[50:51]
	v_pk_mul_f32 v[4:5], v[4:5], v[52:53]
	s_waitcnt vmcnt(2)
	v_pk_add_f32 v[46:47], v[56:57], 1.0 op_sel_hi:[1,0]
	v_pk_add_f32 v[48:49], v[54:55], 1.0 op_sel_hi:[1,0]
	s_waitcnt vmcnt(1)
	v_pk_fma_f32 v[8:9], v[8:9], v[42:43], v[60:61]
	s_waitcnt vmcnt(0)
	v_pk_fma_f32 v[42:43], v[4:5], v[46:47], v[64:65]
	v_pk_fma_f32 v[4:5], v[2:3], v[48:49], v[62:63]
	v_pk_fma_f32 v[6:7], v[6:7], v[44:45], v[58:59]
	s_nop 0
	v_cvt_pk_bf16_f32 v2, v6, v7
	v_cvt_pk_bf16_f32 v3, v8, v9
	v_cvt_pk_bf16_f32 v4, v4, v5
	v_cvt_pk_bf16_f32 v5, v42, v43
	global_store_dwordx4 v[76:77], v[2:5], off offset:1024
	s_branch .LBB0_93
